# ssd_scan: B fragments for the score product read from a row-major LDS copy of the chunk B tile instead of 8 global loads per wave
# speedup vs baseline: 1.0362x; 1.0088x over previous
; DI bf16_t f2bf(float f) { return (bf16_t)(pk2(f, 0.f) & 0xffffu); }
; DI void unpack8(const u32x4& w, float* f) { f[0] = bflo(w.x); f[1] = bfhi(w.x); f[2] = bflo(w.y); f[3] = bfhi(w.y); f[4] = bflo(w.z); f[5] = bfhi(w.z); f[6] = bflo(w.w); f[7] = bfhi(w.w); }
; DI void ssd_scan(const Params& P, LAS unsigned char* lds) {
;     ...
;             float cum = dtv * a;
; #pragma unroll
;             for (int of = 1; of < 64; of <<= 1) { const float o = __shfl_up(cum, of); if (lane >= of) cum += o; }
;             const float cl = __shfl(cum, 63); const float wend = __expf(cl - cum) * dtv;
;             { const int p8 = wid * 8; const bf16_t* e = (const bf16_t*)&xw;
; #pragma unroll
;               for (int j = 0; j < 8; ++j) Xt[(p8 + j) * 72 + lane] = e[j]; }
; #pragma unroll
;             for (int i = 0; i < 2; ++i) { const int n8 = (wid + 8 * i) * 8; float f[8]; unpack8(bw[i], f);
; #pragma unroll
;                 for (int j = 0; j < 8; ++j) BWt[(n8 + j) * 72 + lane] = f2bf(f[j] * wend); }
.LBB0_181:
	s_waitcnt vmcnt(8)
	v_bfe_u32 v216, v107, 6, 3
	v_mul_u32_u24_e32 v217, 0x110, v120
	v_lshl_add_u32 v217, v216, 4, v217
	v_add_u32_e32 v217, 0x1a800, v217
	ds_write_b128 v217, v[74:77]
	ds_write_b128 v217, v[50:53] offset:128
	v_and_b32_e32 v216, 1, v216
	v_and_b32_e32 v218, 15, v107
	v_lshl_add_u32 v216, v216, 5, v218
	v_mul_u32_u24_e32 v218, 0x110, v216
	v_bfe_u32 v216, v107, 4, 2
	v_lshl_add_u32 v218, v216, 4, v218
	v_add_u32_e32 v218, 0x1a800, v218
	v_mul_f32_e64 v78, v113, -v166
	ds_bpermute_b32 v79, v130, v78
	s_waitcnt vmcnt(9)
	v_mov_b64_e32 v[92:93], v[32:33]
	v_mov_b64_e32 v[90:91], v[30:31]
	s_and_b32 s17, s19, 1
	s_mul_i32 s23, s17, 0xd400
	s_waitcnt lgkmcnt(0)
	v_fma_f32 v79, v113, -v166, v79
	v_cndmask_b32_e64 v94, v79, v78, s[38:39]
	ds_bpermute_b32 v95, v131, v94
	s_waitcnt vmcnt(8)
	v_mov_b64_e32 v[80:81], v[18:19]
	v_mov_b64_e32 v[78:79], v[16:17]
	v_mov_b64_e32 v[88:89], v[28:29]
	v_mov_b64_e32 v[84:85], v[22:23]
	s_waitcnt lgkmcnt(0)
	v_add_f32_e32 v16, v94, v95
	v_cndmask_b32_e64 v16, v16, v94, s[40:41]
	ds_bpermute_b32 v17, v132, v16
	v_lshlrev_b32_e32 v18, 16, v74
	s_add_i32 s25, s23, 0
	v_mov_b64_e32 v[86:87], v[26:27]
	v_mov_b64_e32 v[82:83], v[20:21]
	s_waitcnt lgkmcnt(0)
	v_add_f32_e32 v17, v16, v17
	v_cndmask_b32_e64 v16, v17, v16, s[42:43]
	ds_bpermute_b32 v17, v133, v16
	v_and_b32_e32 v19, 0xffff0000, v74
	v_lshlrev_b32_e32 v20, 16, v75
	v_lshl_add_u32 v28, v120, 1, s25
	v_add_u32_e32 v29, s3, v28
	s_waitcnt lgkmcnt(0)
	v_add_f32_e32 v17, v16, v17
	v_cndmask_b32_e64 v16, v17, v16, s[44:45]
	ds_bpermute_b32 v17, v134, v16
	v_and_b32_e32 v21, 0xffff0000, v75
	ds_write_b16 v29, v70 offset:9216
	ds_write_b16_d16_hi v29, v70 offset:9360
	ds_write_b16 v29, v71 offset:9504
	ds_write_b16_d16_hi v29, v71 offset:9648
	ds_write_b16 v29, v72 offset:9792
	ds_write_b16_d16_hi v29, v72 offset:9936
	ds_write_b16 v29, v73 offset:10080
	ds_write_b16_d16_hi v29, v73 offset:10224
	s_waitcnt lgkmcnt(8)
	v_add_f32_e32 v17, v16, v17
	v_cndmask_b32_e64 v16, v17, v16, s[46:47]
	ds_bpermute_b32 v17, v135, v16
	v_lshlrev_b32_e32 v22, 16, v76
	v_and_b32_e32 v23, 0xffff0000, v76
	v_lshlrev_b32_e32 v26, 16, v77
	v_and_b32_e32 v27, 0xffff0000, v77
	s_waitcnt lgkmcnt(0)
	v_add_f32_e32 v17, v16, v17
	v_cndmask_b32_e64 v30, v17, v16, s[48:49]
	ds_bpermute_b32 v170, v123, v30
	ds_bpermute_b32 v174, v136, v30
	ds_bpermute_b32 v173, v137, v30
	ds_bpermute_b32 v172, v138, v30
	ds_bpermute_b32 v171, v139, v30
	s_waitcnt lgkmcnt(4)
	v_sub_f32_e32 v16, v170, v30
	v_mul_f32_e32 v16, 0x3fb8aa3b, v16
	v_exp_f32_e32 v16, v16
	s_xor_b32 s17, s17, 1
	v_add_u32_e32 v118, s18, v169
	v_mov_b64_e32 v[176:177], s[6:7]
	v_mul_f32_e32 v16, v113, v16
	v_mul_f32_e32 v17, v16, v18
	v_mul_f32_e32 v18, v16, v19
	v_mul_f32_e32 v19, v16, v20
	v_cvt_pk_bf16_f32 v17, v17, s0
	v_cvt_pk_bf16_f32 v18, v18, s0
	ds_write_b16 v29, v17 offset:35840
	ds_write_b16 v29, v18 offset:35984
	v_cvt_pk_bf16_f32 v17, v19, s0
	ds_write_b16 v29, v17 offset:36128
	v_mul_f32_e32 v17, v16, v21
	v_cvt_pk_bf16_f32 v17, v17, s0
	ds_write_b16 v29, v17 offset:36272
	v_mul_f32_e32 v17, v16, v22
	v_cvt_pk_bf16_f32 v17, v17, s0
	ds_write_b16 v29, v17 offset:36416
	v_mul_f32_e32 v17, v16, v23
	v_cvt_pk_bf16_f32 v17, v17, s0
	ds_write_b16 v29, v17 offset:36560
	v_mul_f32_e32 v17, v16, v26
	v_cvt_pk_bf16_f32 v17, v17, s0
	ds_write_b16 v29, v17 offset:36704
	v_mul_f32_e32 v17, v16, v27
	v_cvt_pk_bf16_f32 v17, v17, s0
	ds_write_b16 v29, v17 offset:36848
	v_lshlrev_b32_e32 v17, 16, v50
	v_mul_f32_e32 v17, v16, v17
	v_and_b32_e32 v18, 0xffff0000, v50
	v_cvt_pk_bf16_f32 v17, v17, s0
	v_add_u32_e32 v27, s21, v28
	ds_write_b16 v27, v17 offset:35840
	v_mul_f32_e32 v17, v16, v18
	v_lshlrev_b32_e32 v19, 16, v51
	v_cvt_pk_bf16_f32 v17, v17, s0
	ds_write_b16 v29, v17 offset:45200
	v_mul_f32_e32 v17, v16, v19
	v_and_b32_e32 v20, 0xffff0000, v51
	v_cvt_pk_bf16_f32 v17, v17, s0
	ds_write_b16 v29, v17 offset:45344
	v_mul_f32_e32 v17, v16, v20
	v_lshlrev_b32_e32 v21, 16, v52
	v_cvt_pk_bf16_f32 v17, v17, s0
	ds_write_b16 v29, v17 offset:45488
	v_mul_f32_e32 v17, v16, v21
	v_and_b32_e32 v22, 0xffff0000, v52
	v_cvt_pk_bf16_f32 v17, v17, s0
	ds_write_b16 v29, v17 offset:45632
	v_mul_f32_e32 v17, v16, v22
	v_lshlrev_b32_e32 v23, 16, v53
	v_cvt_pk_bf16_f32 v17, v17, s0
	v_and_b32_e32 v26, 0xffff0000, v53
	ds_write_b16 v29, v17 offset:45776
	v_mul_f32_e32 v17, v16, v23
	v_cvt_pk_bf16_f32 v17, v17, s0
	v_mul_f32_e32 v16, v16, v26
	ds_write_b16 v29, v17 offset:45920
	v_cvt_pk_bf16_f32 v20, v16, s0
	s_waitcnt vmcnt(0)
	s_waitcnt lgkmcnt(0)
	s_barrier
; #define LAS __attribute__((address_space(3)))
; DI bf16_t f2bf(float f) { return (bf16_t)(pk2(f, 0.f) & 0xffffu); }
; #define LDS_BARRIER() do { asm volatile("s_waitcnt lgkmcnt(0)" ::: "memory"); __builtin_amdgcn_s_barrier(); asm volatile("" ::: "memory"); } while (0)
; #define MFMA16(a, b, c) __builtin_amdgcn_mfma_f32_16x16x32_bf16((a), (b), (c), 0, 0, 0)
; DI void ssd_scan(const Params& P, LAS unsigned char* lds) {
;     ...
; #pragma unroll
;             for (int j = 0; j < 4; ++j) cumt[j] = __shfl(cum, 16 * mb + 4 * fq + j);
; #pragma unroll
;             for (int i = 0; i < 2; ++i) { const int nb = 2 * hb + i; f32x4 sc = {0.f, 0.f, 0.f, 0.f};
; #pragma unroll
;                 for (int ks = 0; ks < 4; ++ks) sc = MFMA16(ca[ks], bbf[i][ks], sc);
;                 const int s = 16 * nb + fr; const float cums = __shfl(cum, s), dts = __shfl(dtv, s);
; #pragma unroll
;                 for (int j = 0; j < 4; ++j) { const int t = 16 * mb + 4 * fq + j; Pm[t * 72 + s] = f2bf(s <= t ? sc[j] * __expf(cumt[j] - cums) * dts : 0.f); } }
;             LDS_BARRIER();
;             float dtn = dtv; bf16x8 cn[4];
; #pragma unroll
;             for (int ks = 0; ks < 4; ++ks) cn[ks] = ca[ks];
;             if (n + 1 < 32) SSD_LOAD(row0 + 64, dtn, cn);
;             f32x4 yi[2], ye[2];
; #pragma unroll
;             for (int i = 0; i < 2; ++i) { yi[i] = (f32x4){0.f, 0.f, 0.f, 0.f}; ye[i] = (f32x4){0.f, 0.f, 0.f, 0.f}; }
; #pragma unroll
;             for (int k2 = 0; k2 < 2; ++k2) { const bf16x8 am = *(const LAS bf16x8*)(Pm + (16 * mb + fr) * 72 + 32 * k2 + 8 * fq);
; #pragma unroll
;                 for (int i = 0; i < 2; ++i) { const bf16x8 bb = *(const LAS bf16x8*)(Xt + (16 * (2 * hb + i) + fr) * 72 + 32 * k2 + 8 * fq); yi[i] = MFMA16(am, bb, yi[i]); } }
	ds_read_b128 v[54:57], v218
	ds_read_b128 v[58:61], v218 offset:64
	ds_read_b128 v[66:69], v218 offset:128
	ds_read_b128 v[62:65], v218 offset:192
	ds_read_b128 v[46:49], v218 offset:4352
	ds_read_b128 v[38:41], v218 offset:4416
	ds_read_b128 v[42:45], v218 offset:4480
	ds_read_b128 v[34:37], v218 offset:4544
	s_waitcnt lgkmcnt(0)
	s_waitcnt vmcnt(5)
	v_mfma_f32_16x16x32_bf16 v[16:19], v[90:93], v[54:57], 0
	ds_write_b16 v29, v20 offset:46064
	ds_bpermute_b32 v20, v140, v30
	ds_bpermute_b32 v26, v140, v113
	v_mfma_f32_16x16x32_bf16 v[16:19], v[86:89], v[58:61], v[16:19]
	v_add3_u32 v27, s25, v102, v141
	s_mul_i32 s23, s17, 0xd400
	s_waitcnt lgkmcnt(1)
	v_sub_f32_e32 v21, v174, v20
	v_mfma_f32_16x16x32_bf16 v[16:19], v[82:85], v[66:69], v[16:19]
	v_mul_f32_e32 v21, 0x3fb8aa3b, v21
	v_exp_f32_e32 v21, v21
	s_mov_b32 s17, s37
	s_waitcnt vmcnt(4)
	v_mfma_f32_16x16x32_bf16 v[16:19], v[78:81], v[62:65], v[16:19]
	v_add_u32_e32 v175, s25, v24
	v_add_u32_e32 v58, v175, v146
	v_add3_u32 v214, s25, v126, v148
	v_ashrrev_i32_e32 v119, 31, v118
	s_add_i32 s19, s19, 1
	s_nop 2
	v_mul_f32_e32 v16, v16, v21
	v_sub_f32_e32 v21, v173, v20
	v_mul_f32_e32 v21, 0x3fb8aa3b, v21
	v_exp_f32_e32 v21, v21
	s_waitcnt lgkmcnt(0)
	v_mul_f32_e32 v16, v16, v26
	v_cvt_pk_bf16_f32 v16, v16, s0
	v_cndmask_b32_e64 v16, v16, 0, s[50:51]
	ds_write_b16 v27, v16
	v_mul_f32_e32 v16, v17, v21
	v_sub_f32_e32 v17, v172, v20
	v_mul_f32_e32 v17, 0x3fb8aa3b, v17
	v_exp_f32_e32 v17, v17
	v_mul_f32_e32 v16, v16, v26
	v_cvt_pk_bf16_f32 v16, v16, s0
	v_cndmask_b32_e64 v16, v16, 0, s[52:53]
	ds_write_b16 v27, v16 offset:144
	v_mul_f32_e32 v16, v18, v17
	v_sub_f32_e32 v17, v171, v20
	v_mul_f32_e32 v17, 0x3fb8aa3b, v17
	v_exp_f32_e32 v17, v17
	v_mul_f32_e32 v16, v16, v26
	v_cvt_pk_bf16_f32 v16, v16, s0
	s_waitcnt vmcnt(1)
	v_mfma_f32_16x16x32_bf16 v[20:23], v[90:93], v[46:49], 0
	v_cndmask_b32_e64 v16, v16, 0, s[54:55]
	ds_write_b16 v27, v16 offset:288
	v_mul_f32_e32 v16, v19, v17
	v_mul_f32_e32 v16, v16, v26
	v_cvt_pk_bf16_f32 v26, v16, s0
	v_mfma_f32_16x16x32_bf16 v[16:19], v[86:89], v[38:41], v[20:23]
	v_add_u32_e32 v46, v175, v125
	s_nop 1
	ds_bpermute_b32 v20, v145, v30
	v_mfma_f32_16x16x32_bf16 v[16:19], v[82:85], v[42:45], v[16:19]
	v_cndmask_b32_e64 v21, v26, 0, s[56:57]
	ds_write_b16 v27, v21 offset:432
	ds_bpermute_b32 v21, v145, v113
	s_waitcnt lgkmcnt(2)
	v_sub_f32_e32 v22, v174, v20
	v_mul_f32_e32 v22, 0x3fb8aa3b, v22
	v_exp_f32_e32 v22, v22
	s_waitcnt vmcnt(0)
	v_mfma_f32_16x16x32_bf16 v[16:19], v[78:81], v[34:37], v[16:19]
	v_add_u32_e32 v113, s18, v165
	v_add_u32_e32 v38, 64, v113
	v_mad_i64_i32 v[42:43], s[66:67], v38, s87, v[176:177]
	v_lshl_add_u64 v[42:43], v[42:43], 0, s[16:17]
	s_nop 3
	v_mul_f32_e32 v16, v16, v22
	v_sub_f32_e32 v22, v173, v20
	v_mul_f32_e32 v22, 0x3fb8aa3b, v22
	v_exp_f32_e32 v22, v22
	s_waitcnt lgkmcnt(0)
	v_mul_f32_e32 v16, v16, v21
	v_cvt_pk_bf16_f32 v16, v16, s0
	v_cndmask_b32_e64 v16, v16, 0, s[58:59]
	ds_write_b16 v27, v16 offset:32
	v_mul_f32_e32 v16, v17, v22
	v_sub_f32_e32 v17, v172, v20
	v_mul_f32_e32 v17, 0x3fb8aa3b, v17
	v_exp_f32_e32 v17, v17
	v_mul_f32_e32 v16, v16, v21
	v_cvt_pk_bf16_f32 v16, v16, s0
	v_cndmask_b32_e64 v16, v16, 0, s[60:61]
	ds_write_b16 v27, v16 offset:176
	v_mul_f32_e32 v16, v18, v17
	v_sub_f32_e32 v17, v171, v20
	v_mul_f32_e32 v17, 0x3fb8aa3b, v17
	v_exp_f32_e32 v17, v17
	v_mul_f32_e32 v16, v16, v21
	v_cvt_pk_bf16_f32 v16, v16, s0
	v_cndmask_b32_e64 v16, v16, 0, s[62:63]
	ds_write_b16 v27, v16 offset:320
	v_mul_f32_e32 v16, v19, v17
	v_mul_f32_e32 v16, v16, v21
	v_cvt_pk_bf16_f32 v16, v16, s0
	v_cndmask_b32_e64 v16, v16, 0, s[64:65]
	ds_write_b16 v27, v16 offset:464
	v_mad_i64_i32 v[16:17], s[66:67], v118, s87, v[176:177]
	v_lshl_add_u64 v[18:19], v[16:17], 0, s[36:37]
	v_lshl_add_u64 v[16:17], v[16:17], 0, s[16:17]
	s_waitcnt lgkmcnt(0)
	s_barrier
	v_lshl_add_u64 v[18:19], v[18:19], 0, s[12:13]
	v_lshl_add_u64 v[16:17], v[16:17], 0, s[12:13]
	global_load_dwordx4 v[70:73], v[18:19], off
	v_lshl_add_u64 v[18:19], v[16:17], 0, s[70:71]
	v_add_co_u32_e32 v16, vcc, s86, v16
	v_lshl_add_u64 v[54:55], v[42:43], 0, v[24:25]
	s_nop 0
	v_addc_co_u32_e32 v17, vcc, 0, v17, vcc
	global_load_dwordx4 v[74:77], v[16:17], off
	global_load_dwordx4 v[50:53], v[18:19], off offset:128
	v_add_u32_e32 v16, s18, v168
	v_mad_i64_i32 v[16:17], s[66:67], v16, s87, v[176:177]
	v_lshl_add_u64 v[16:17], v[16:17], 0, s[16:17]
	v_lshl_add_u64 v[16:17], v[16:17], 0, v[24:25]
	v_lshl_add_u64 v[18:19], v[16:17], 0, s[96:97]
	v_add_co_u32_e32 v16, vcc, s86, v16
	v_lshl_add_u64 v[178:179], v[54:55], 0, s[70:71]
	s_nop 0
	v_addc_co_u32_e32 v17, vcc, 0, v17, vcc
	global_load_dwordx4 v[30:33], v[16:17], off offset:1024
	global_load_dwordx4 v[26:29], v[18:19], off offset:64
	global_load_dwordx4 v[20:23], v[18:19], off offset:128
	s_nop 0
	global_load_dwordx4 v[16:19], v[18:19], off offset:192
	ds_read_b128 v[34:37], v46
	ds_read_b128 v[38:41], v58 offset:9216
	ds_read_b128 v[42:45], v58 offset:11520
	ds_read_b128 v[62:65], v58 offset:11584
	ds_read_b128 v[46:49], v46 offset:64
	s_waitcnt lgkmcnt(3)
	v_mfma_f32_16x16x32_bf16 v[38:41], v[34:37], v[38:41], 0
	v_add_co_u32_e32 v54, vcc, s86, v54
	v_lshlrev_b64 v[118:119], 7, v[118:119]
	s_waitcnt lgkmcnt(2)
	v_mfma_f32_16x16x32_bf16 v[34:37], v[34:37], v[42:45], 0
	ds_read_b128 v[42:45], v58 offset:9280
	v_addc_co_u32_e32 v55, vcc, 0, v55, vcc
	s_waitcnt lgkmcnt(0)
	v_mfma_f32_16x16x32_bf16 v[98:101], v[46:49], v[42:45], v[38:41]
	v_add_u32_e32 v42, 0x50, v113
	s_nop 1
	ds_read_b128 v[38:41], v214 offset:18432
	v_mad_i64_i32 v[42:43], s[66:67], v42, s87, v[176:177]
	s_nop 0
	v_mfma_f32_16x16x32_bf16 v[94:97], v[46:49], v[62:65], v[34:37]
	s_nop 0
	s_nop 0
	s_nop 0
	v_lshl_add_u64 v[46:47], v[42:43], 0, s[16:17]
	s_waitcnt lgkmcnt(0)
; #define LAS __attribute__((address_space(3)))
; DI unsigned pk2(float lo, float hi) { const f32x2v v = {lo, hi}; const bf16x2v b = __builtin_convertvector(v, bf16x2v); return __builtin_bit_cast(unsigned, b); }
; DI float bf2f(bf16_t b) { return __uint_as_float(((unsigned)b) << 16); }
; DI bf16_t f2bf(float f) { return (bf16_t)(pk2(f, 0.f) & 0xffffu); }
; #define MFMA16(a, b, c) __builtin_amdgcn_mfma_f32_16x16x32_bf16((a), (b), (c), 0, 0, 0)
; DI void ssd_scan(const Params& P, LAS unsigned char* lds) {
;     ...
; #pragma unroll
;             for (int ks = 0; ks < 4; ++ks)
; #pragma unroll
;                 for (int i = 0; i < 2; ++i) { const bf16x8 bb = *(const LAS bf16x8*)(Sb + (16 * (2 * hb + i) + fr) * 136 + 32 * ks + 8 * fq); ye[i] = MFMA16(ca[ks], bb, ye[i]); }
; #pragma unroll
;             for (int j = 0; j < 4; ++j) { const int tl = 16 * mb + 4 * fq + j, row = row0 + tl; const float ec = __expf(cumt[j]);
; #pragma unroll
;                 for (int i = 0; i < 2; ++i) { const int p = 16 * (2 * hb + i) + fr; const float xv = bf2f(Xt[p * 72 + tl]);
;                     YB[(size_t)row * 2048 + h * 64 + p] = f2bf(yi[i][j] + ec * ye[i][j] + dsk * xv); } }
;             { const float ecl = __expf(cl);
; #pragma unroll
;               for (int i = 0; i < 4; ++i) Sacc[i] *= ecl; }
; #pragma unroll
;             for (int k2 = 0; k2 < 2; ++k2) { const bf16x8 am = *(const LAS bf16x8*)(BWt + (16 * wid + fr) * 72 + 32 * k2 + 8 * fq);
; #pragma unroll
;                 for (int i = 0; i < 4; ++i) { const bf16x8 bb = *(const LAS bf16x8*)(Xt + (16 * i + fr) * 72 + 32 * k2 + 8 * fq); Sacc[i] = MFMA16(am, bb, Sacc[i]); } }
; #pragma unroll
;             for (int i = 0; i < 4; ++i) { u32x2 w; w.x = pk2(Sacc[i][0], Sacc[i][1]); w.y = pk2(Sacc[i][2], Sacc[i][3]); *(LAS u32x2*)(Sbn + (16 * i + fr) * 136 + 16 * wid + 4 * fq) = w; }
;             dtv = dtn;
; #pragma unroll
;             for (int ks = 0; ks < 4; ++ks) ca[ks] = cn[ks];
	v_mfma_f32_16x16x32_bf16 v[34:37], v[90:93], v[38:41], 0
	ds_read_b128 v[38:41], v214 offset:22784
	ds_read_b128 v[42:45], v214 offset:18496
	v_lshl_add_u64 v[118:119], s[14:15], 0, v[118:119]
	s_waitcnt lgkmcnt(1)
	v_mfma_f32_16x16x32_bf16 v[38:41], v[90:93], v[38:41], 0
	v_lshl_add_u64 v[90:91], v[46:47], 0, v[24:25]
	ds_read_b128 v[46:49], v214 offset:22848
	v_add_co_u32_e32 v180, vcc, s86, v90
	s_waitcnt lgkmcnt(1)
	v_mfma_f32_16x16x32_bf16 v[34:37], v[86:89], v[42:45], v[34:37]
	ds_read_b128 v[42:45], v214 offset:18560
	v_lshl_add_u64 v[212:213], v[90:91], 0, s[70:71]
	v_addc_co_u32_e32 v181, vcc, 0, v91, vcc
	s_waitcnt lgkmcnt(1)
	v_mfma_f32_16x16x32_bf16 v[86:89], v[86:89], v[46:49], v[38:41]
	ds_read_b128 v[90:93], v214 offset:22912
	s_nop 0
	s_nop 0
	s_nop 0
	ds_read_b128 v[180:183], v214 offset:18624
	s_waitcnt lgkmcnt(2)
	v_mfma_f32_16x16x32_bf16 v[176:179], v[82:85], v[42:45], v[34:37]
	s_nop 0
	s_nop 1
	s_nop 0
	global_load_dword v113, v[118:119], off
	s_waitcnt lgkmcnt(1)
	v_mfma_f32_16x16x32_bf16 v[82:85], v[82:85], v[90:93], v[86:89]
	s_nop 2
	ds_read_b128 v[86:89], v214 offset:22976
	s_waitcnt lgkmcnt(1)
	v_mfma_f32_16x16x32_bf16 v[90:93], v[78:81], v[180:183], v[176:179]
	s_waitcnt lgkmcnt(0)
	v_mfma_f32_16x16x32_bf16 v[78:81], v[78:81], v[86:89], v[82:85]
	v_add_u32_e32 v86, s18, v109
	v_ashrrev_i32_e32 v87, 31, v86
	s_add_i32 s18, s18, 64
	v_lshlrev_b32_e32 v82, 1, v124
	v_add3_u32 v82, s25, v82, v146
	ds_read_b64 v[84:85], v82 offset:9216
	v_mul_f32_e32 v83, 0x3fb8aa3b, v174
	v_exp_f32_e32 v174, v83
	s_cmpk_eq_i32 s18, 0x7c0
	s_waitcnt lgkmcnt(0)
	v_lshlrev_b32_e32 v83, 16, v84
	v_fma_f32 v88, v174, v90, v98
	v_fmac_f32_e32 v88, v111, v83
	ds_read_b64 v[82:83], v82 offset:11520
	v_cvt_pk_bf16_f32 v90, v88, s0
	v_lshlrev_b64 v[88:89], 12, v[86:87]
	v_fma_f32 v78, v174, v78, v94
	v_lshl_add_u64 v[118:119], v[114:115], 0, v[88:89]
	s_waitcnt lgkmcnt(0)
	v_lshlrev_b32_e32 v87, 16, v82
	v_fmac_f32_e32 v78, v111, v87
	v_cvt_pk_bf16_f32 v78, v78, s0
	v_lshl_add_u64 v[88:89], v[116:117], 0, v[88:89]
	global_store_short v[88:89], v78, off
	v_mul_f32_e32 v78, 0x3fb8aa3b, v173
	v_exp_f32_e32 v78, v78
	v_add_u32_e32 v88, 1, v86
	v_ashrrev_i32_e32 v89, 31, v88
	v_and_b32_e32 v82, 0xffff0000, v82
	v_fma_f32 v87, v78, v91, v99
	v_fma_f32 v78, v78, v79, v95
	v_lshlrev_b64 v[88:89], 12, v[88:89]
	v_fmac_f32_e32 v78, v111, v82
	v_cvt_pk_bf16_f32 v82, v78, s0
	v_lshl_add_u64 v[78:79], v[116:117], 0, v[88:89]
	global_store_short v[78:79], v82, off
	v_mul_f32_e32 v78, 0x3fb8aa3b, v172
	v_exp_f32_e32 v82, v78
	v_and_b32_e32 v84, 0xffff0000, v84
	v_fmac_f32_e32 v87, v111, v84
	global_store_short v[118:119], v90, off
	v_cvt_pk_bf16_f32 v84, v87, s0
	v_lshl_add_u64 v[90:91], v[114:115], 0, v[88:89]
	v_add_u32_e32 v78, 2, v86
	global_store_short v[90:91], v84, off
	v_ashrrev_i32_e32 v79, 31, v78
	v_lshlrev_b32_e32 v84, 16, v85
	v_fma_f32 v87, v82, v92, v100
	v_fmac_f32_e32 v87, v111, v84
	v_lshlrev_b64 v[78:79], 12, v[78:79]
	v_cvt_pk_bf16_f32 v84, v87, s0
	v_lshl_add_u64 v[88:89], v[114:115], 0, v[78:79]
	global_store_short v[88:89], v84, off
	v_lshlrev_b32_e32 v84, 16, v83
	v_fma_f32 v80, v82, v80, v96
	v_fmac_f32_e32 v80, v111, v84
	v_cvt_pk_bf16_f32 v80, v80, s0
	v_lshl_add_u64 v[78:79], v[116:117], 0, v[78:79]
	global_store_short v[78:79], v80, off
	v_mul_f32_e32 v78, 0x3fb8aa3b, v171
	v_exp_f32_e32 v82, v78
	v_add_u32_e32 v96, v175, v127
	v_add_u32_e32 v78, 3, v86
	v_and_b32_e32 v80, 0xffff0000, v85
	ds_read_b128 v[84:87], v96 offset:35840
	v_fmac_f32_e32 v101, v82, v93
	v_fmac_f32_e32 v101, v111, v80
	v_mul_f32_e32 v80, 0x3fb8aa3b, v170
	v_add_u32_e32 v119, v175, v149
	v_exp_f32_e32 v80, v80
	ds_read_b128 v[88:91], v119 offset:9216
	ds_read_b128 v[92:95], v119 offset:11520
	v_cvt_pk_bf16_f32 v118, v101, s0
	v_pk_mul_f32 v[2:3], v[2:3], v[80:81] op_sel_hi:[1,0]
	v_pk_mul_f32 v[0:1], v[0:1], v[80:81] op_sel_hi:[1,0]
	v_pk_mul_f32 v[6:7], v[6:7], v[80:81] op_sel_hi:[1,0]
	v_pk_mul_f32 v[4:5], v[4:5], v[80:81] op_sel_hi:[1,0]
	s_waitcnt lgkmcnt(1)
	v_mfma_f32_16x16x32_bf16 v[0:3], v[84:87], v[88:91], v[0:3]
	ds_read_b128 v[88:91], v119 offset:13824
	v_pk_mul_f32 v[14:15], v[14:15], v[80:81] op_sel_hi:[1,0]
	v_pk_mul_f32 v[12:13], v[12:13], v[80:81] op_sel_hi:[1,0]
	s_waitcnt lgkmcnt(1)
	v_mfma_f32_16x16x32_bf16 v[4:7], v[84:87], v[92:95], v[4:7]
	ds_read_b128 v[92:95], v119 offset:16128
	ds_read_b128 v[98:101], v96 offset:35904
	v_ashrrev_i32_e32 v79, 31, v78
	v_pk_mul_f32 v[10:11], v[10:11], v[80:81] op_sel_hi:[1,0]
	s_waitcnt lgkmcnt(2)
	v_mfma_f32_16x16x32_bf16 v[12:15], v[84:87], v[88:91], v[12:15]
	ds_read_b128 v[88:91], v119 offset:9280
	v_pk_mul_f32 v[8:9], v[8:9], v[80:81] op_sel_hi:[1,0]
	v_fmac_f32_e32 v97, v82, v81
	s_waitcnt lgkmcnt(2)
	v_mfma_f32_16x16x32_bf16 v[8:11], v[84:87], v[92:95], v[8:11]
	v_lshlrev_b64 v[92:93], 12, v[78:79]
	v_lshl_add_u64 v[78:79], v[114:115], 0, v[92:93]
	ds_read_b128 v[84:87], v119 offset:11584
	s_waitcnt lgkmcnt(1)
	v_mfma_f32_16x16x32_bf16 v[0:3], v[98:101], v[88:91], v[0:3]
	global_store_short v[78:79], v118, off
	v_and_b32_e32 v78, 0xffff0000, v83
	ds_read_b128 v[88:91], v119 offset:13888
	v_fmac_f32_e32 v97, v111, v78
	ds_read_b128 v[78:81], v119 offset:16192
	s_waitcnt lgkmcnt(2)
	v_mfma_f32_16x16x32_bf16 v[4:7], v[98:101], v[84:87], v[4:7]
	v_cvt_pk_bf16_f32 v84, v97, s0
	v_lshl_add_u64 v[82:83], v[116:117], 0, v[92:93]
	global_store_short v[82:83], v84, off
	s_waitcnt lgkmcnt(1)
	v_mfma_f32_16x16x32_bf16 v[12:15], v[98:101], v[88:91], v[12:15]
	s_waitcnt lgkmcnt(0)
	v_mfma_f32_16x16x32_bf16 v[8:11], v[98:101], v[78:81], v[8:11]
	v_cvt_pk_bf16_f32 v78, v0, v1
	v_cvt_pk_bf16_f32 v79, v2, v3
	v_add3_u32 v80, v154, s23, v150
	ds_write_b64 v80, v[78:79] offset:18432
	v_cvt_pk_bf16_f32 v78, v4, v5
	v_cvt_pk_bf16_f32 v79, v6, v7
	ds_write_b64 v80, v[78:79] offset:22784
	v_cvt_pk_bf16_f32 v78, v12, v13
	v_cvt_pk_bf16_f32 v79, v14, v15
	ds_write_b64 v80, v[78:79] offset:27136
	v_cvt_pk_bf16_f32 v78, v8, v9
	v_cvt_pk_bf16_f32 v79, v10, v11
	ds_write_b64 v80, v[78:79] offset:31488
	s_cbranch_scc0 .LBB0_181
; #define LAS __attribute__((address_space(3)))
; DI bf16_t f2bf(float f) { return (bf16_t)(pk2(f, 0.f) & 0xffffu); }
; DI void unpack8(const u32x4& w, float* f) { f[0] = bflo(w.x); f[1] = bfhi(w.x); f[2] = bflo(w.y); f[3] = bfhi(w.y); f[4] = bflo(w.z); f[5] = bfhi(w.z); f[6] = bflo(w.w); f[7] = bfhi(w.w); }
; #define MFMA16(a, b, c) __builtin_amdgcn_mfma_f32_16x16x32_bf16((a), (b), (c), 0, 0, 0)
; DI void ssd_scan(const Params& P, LAS unsigned char* lds) {
;     ...
;         for (int n = 0; n < 32; ++n) {
;             const int row0 = b * 2048 + 64 * n;
;             LAS unsigned char* sb_ = lds + (n & 1) * SSET; LAS unsigned char* so_ = lds + ((n & 1) ^ 1) * SSET;
;             LAS bf16_t* Pm = (LAS bf16_t*)sb_; LAS bf16_t* Xt = (LAS bf16_t*)(sb_ + 9216); LAS bf16_t* Sb = (LAS bf16_t*)(sb_ + 18432); LAS bf16_t* BWt = (LAS bf16_t*)(sb_ + 35840);
;             LAS bf16_t* Sbn = (LAS bf16_t*)(so_ + 18432);
;             float cum = dtv * a;
; #pragma unroll
;             for (int of = 1; of < 64; of <<= 1) { const float o = __shfl_up(cum, of); if (lane >= of) cum += o; }
;             const float cl = __shfl(cum, 63); const float wend = __expf(cl - cum) * dtv;
;             { const int p8 = wid * 8; const bf16_t* e = (const bf16_t*)&xw;
; #pragma unroll
;               for (int j = 0; j < 8; ++j) Xt[(p8 + j) * 72 + lane] = e[j]; }
; #pragma unroll
;             for (int i = 0; i < 2; ++i) { const int n8 = (wid + 8 * i) * 8; float f[8]; unpack8(bw[i], f);
; #pragma unroll
;                 for (int j = 0; j < 8; ++j) BWt[(n8 + j) * 72 + lane] = f2bf(f[j] * wend); }
;             float cumt[4];
; #pragma unroll
;             for (int j = 0; j < 4; ++j) cumt[j] = __shfl(cum, 16 * mb + 4 * fq + j);
; #pragma unroll
;             for (int i = 0; i < 2; ++i) { const int nb = 2 * hb + i; f32x4 sc = {0.f, 0.f, 0.f, 0.f};
; #pragma unroll
;                 for (int ks = 0; ks < 4; ++ks) sc = MFMA16(ca[ks], bbf[i][ks], sc);
;                 const int s = 16 * nb + fr; const float cums = __shfl(cum, s), dts = __shfl(dtv, s);
; #pragma unroll
;                 for (int j = 0; j < 4; ++j) { const int t = 16 * mb + 4 * fq + j; Pm[t * 72 + s] = f2bf(s <= t ? sc[j] * __expf(cumt[j] - cums) * dts : 0.f); } }
	s_waitcnt vmcnt(8)
	v_bfe_u32 v216, v107, 6, 3
	v_mul_u32_u24_e32 v217, 0x110, v120
	v_lshl_add_u32 v217, v216, 4, v217
	v_add_u32_e32 v217, 0x1a800, v217
	ds_write_b128 v217, v[74:77]
	ds_write_b128 v217, v[50:53] offset:128
	v_and_b32_e32 v216, 1, v216
	v_and_b32_e32 v218, 15, v107
	v_lshl_add_u32 v216, v216, 5, v218
	v_mul_u32_u24_e32 v218, 0x110, v216
	v_bfe_u32 v216, v107, 4, 2
	v_lshl_add_u32 v218, v216, 4, v218
	v_add_u32_e32 v218, 0x1a800, v218
	s_waitcnt vmcnt(0)
	s_waitcnt lgkmcnt(0)
	s_barrier
	ds_read_b128 v[54:57], v218
	ds_read_b128 v[58:61], v218 offset:64
	ds_read_b128 v[66:69], v218 offset:128
	ds_read_b128 v[62:65], v218 offset:192
	ds_read_b128 v[46:49], v218 offset:4352
	ds_read_b128 v[38:41], v218 offset:4416
	ds_read_b128 v[42:45], v218 offset:4480
	ds_read_b128 v[34:37], v218 offset:4544
	s_waitcnt lgkmcnt(0)
	v_mul_f32_e64 v78, v113, -v166
	ds_bpermute_b32 v79, v130, v78
	ds_write_b16 v159, v70 offset:63488
	ds_write_b16_d16_hi v159, v70 offset:63632
	ds_write_b16 v159, v71 offset:63776
	ds_write_b16_d16_hi v159, v71 offset:63920
	ds_write_b16 v159, v72 offset:64064
	ds_write_b16_d16_hi v159, v72 offset:64208
	ds_write_b16 v159, v73 offset:64352
	ds_write_b16_d16_hi v159, v73 offset:64496
	v_lshlrev_b32_e32 v71, 16, v74
	v_and_b32_e32 v72, 0xffff0000, v74
	v_add_u32_e32 v81, s3, v151
	s_waitcnt lgkmcnt(8)
	v_fma_f32 v79, v113, -v166, v79
	v_cndmask_b32_e64 v78, v79, v78, s[38:39]
	ds_bpermute_b32 v79, v131, v78
	v_lshlrev_b32_e32 v73, 16, v75
	v_and_b32_e32 v74, 0xffff0000, v75
	v_lshlrev_b32_e32 v75, 16, v76
	v_and_b32_e32 v76, 0xffff0000, v76
	s_waitcnt lgkmcnt(0)
	v_add_f32_e32 v79, v78, v79
	v_cndmask_b32_e64 v78, v79, v78, s[40:41]
	ds_bpermute_b32 v79, v132, v78
	v_mfma_f32_16x16x32_bf16 v[46:49], v[30:33], v[46:49], 0
	s_or_b32 s5, s5, 0x7c0
	s_waitcnt lgkmcnt(0)
	v_add_f32_e32 v79, v78, v79
	v_cndmask_b32_e64 v78, v79, v78, s[42:43]
	ds_bpermute_b32 v79, v133, v78
	v_mfma_f32_16x16x32_bf16 v[38:41], v[26:29], v[38:41], v[46:49]
	s_waitcnt lgkmcnt(0)
	v_add_f32_e32 v79, v78, v79
	v_cndmask_b32_e64 v78, v79, v78, s[44:45]
	ds_bpermute_b32 v79, v134, v78
	v_mfma_f32_16x16x32_bf16 v[54:57], v[30:33], v[54:57], 0
	s_waitcnt lgkmcnt(0)
	v_add_f32_e32 v79, v78, v79
	v_cndmask_b32_e64 v78, v79, v78, s[46:47]
	ds_bpermute_b32 v79, v135, v78
	v_mfma_f32_16x16x32_bf16 v[38:41], v[20:23], v[42:45], v[38:41]
	s_waitcnt lgkmcnt(0)
	v_add_f32_e32 v79, v78, v79
	v_cndmask_b32_e64 v79, v79, v78, s[48:49]
	ds_bpermute_b32 v78, v123, v79
	v_mfma_f32_16x16x32_bf16 v[54:57], v[26:29], v[58:61], v[54:57]
	ds_bpermute_b32 v58, v140, v79
	ds_bpermute_b32 v59, v140, v113
	s_waitcnt lgkmcnt(2)
	v_sub_f32_e32 v80, v78, v79
	v_mul_f32_e32 v80, 0x3fb8aa3b, v80
	v_exp_f32_e32 v80, v80
	v_mfma_f32_16x16x32_bf16 v[34:37], v[16:19], v[34:37], v[38:41]
	v_mul_f32_e32 v70, v113, v80
	v_mul_f32_e32 v71, v70, v71
	v_cvt_pk_bf16_f32 v71, v71, s0
	ds_write_b16 v81, v71
	v_mul_f32_e32 v71, v70, v72
	v_cvt_pk_bf16_f32 v71, v71, s0
	ds_write_b16 v81, v71 offset:144
	v_mul_f32_e32 v71, v70, v73
	v_cvt_pk_bf16_f32 v71, v71, s0
	ds_write_b16 v81, v71 offset:288
	v_mul_f32_e32 v71, v70, v74
	v_cvt_pk_bf16_f32 v71, v71, s0
	ds_write_b16 v81, v71 offset:432
	v_mul_f32_e32 v71, v70, v75
	v_cvt_pk_bf16_f32 v71, v71, s0
	ds_write_b16 v81, v71 offset:576
	v_mul_f32_e32 v71, v70, v76
	v_lshlrev_b32_e32 v80, 16, v77
	v_cvt_pk_bf16_f32 v71, v71, s0
	ds_write_b16 v81, v71 offset:720
	v_mul_f32_e32 v71, v70, v80
	v_and_b32_e32 v77, 0xffff0000, v77
	v_cvt_pk_bf16_f32 v71, v71, s0
	ds_write_b16 v81, v71 offset:864
	v_mul_f32_e32 v71, v70, v77
	v_cvt_pk_bf16_f32 v71, v71, s0
	ds_write_b16 v81, v71 offset:1008
	v_lshlrev_b32_e32 v71, 16, v50
	v_and_b32_e32 v50, 0xffff0000, v50
	v_mul_f32_e32 v50, v70, v50
	v_lshlrev_b32_e32 v72, 16, v51
	v_cvt_pk_bf16_f32 v50, v50, s0
	ds_write_b16 v81, v50 offset:9360
	v_mul_f32_e32 v50, v70, v72
	v_and_b32_e32 v51, 0xffff0000, v51
	v_cvt_pk_bf16_f32 v50, v50, s0
	ds_write_b16 v81, v50 offset:9504
	v_mul_f32_e32 v50, v70, v51
	v_lshlrev_b32_e32 v73, 16, v52
	v_cvt_pk_bf16_f32 v50, v50, s0
	ds_write_b16 v81, v50 offset:9648
	v_mul_f32_e32 v50, v70, v73
	v_and_b32_e32 v52, 0xffff0000, v52
	v_cvt_pk_bf16_f32 v50, v50, s0
	ds_write_b16 v81, v50 offset:9792
	v_mul_f32_e32 v50, v70, v52
	v_lshlrev_b32_e32 v74, 16, v53
	v_cvt_pk_bf16_f32 v50, v50, s0
	ds_write_b16 v81, v50 offset:9936
	v_mul_f32_e32 v50, v70, v74
	v_and_b32_e32 v53, 0xffff0000, v53
	v_cvt_pk_bf16_f32 v50, v50, s0
	ds_write_b16 v81, v50 offset:10080
	v_mul_f32_e32 v50, v70, v53
	ds_bpermute_b32 v53, v136, v79
	ds_bpermute_b32 v38, v145, v79
	v_mfma_f32_16x16x32_bf16 v[54:57], v[20:23], v[66:69], v[54:57]
	ds_bpermute_b32 v39, v145, v113
	ds_bpermute_b32 v52, v137, v79
	s_waitcnt lgkmcnt(3)
	v_sub_f32_e32 v60, v53, v58
	s_waitcnt lgkmcnt(2)
	v_sub_f32_e32 v40, v53, v38
	v_mul_f32_e32 v60, 0x3fb8aa3b, v60
	v_mul_f32_e32 v40, 0x3fb8aa3b, v40
	v_mfma_f32_16x16x32_bf16 v[54:57], v[16:19], v[62:65], v[54:57]
	v_exp_f32_e32 v60, v60
	v_exp_f32_e32 v40, v40
	v_mul_f32_e32 v71, v70, v71
	v_cvt_pk_bf16_f32 v71, v71, s0
	v_add_u32_e32 v75, s21, v151
	s_nop 2
	v_mul_f32_e32 v54, v54, v60
	v_mul_f32_e32 v34, v34, v40
	v_mul_f32_e32 v54, v54, v59
	s_waitcnt lgkmcnt(1)
	v_mul_f32_e32 v34, v34, v39
	v_cvt_pk_bf16_f32 v54, v54, s0
	v_cvt_pk_bf16_f32 v34, v34, s0
	v_cvt_pk_bf16_f32 v50, v50, s0
	v_cndmask_b32_e64 v54, v54, 0, s[50:51]
	v_cndmask_b32_e64 v34, v34, 0, s[58:59]
	ds_write_b16 v75, v71
	ds_write_b16 v81, v50 offset:10224
	ds_write_b16 v160, v54 offset:54272
	s_waitcnt lgkmcnt(3)
; #define LAS __attribute__((address_space(3)))
; DI float bf2f(bf16_t b) { return __uint_as_float(((unsigned)b) << 16); }
; DI bf16_t f2bf(float f) { return (bf16_t)(pk2(f, 0.f) & 0xffffu); }
; #define LDS_BARRIER() do { asm volatile("s_waitcnt lgkmcnt(0)" ::: "memory"); __builtin_amdgcn_s_barrier(); asm volatile("" ::: "memory"); } while (0)
; #define MFMA16(a, b, c) __builtin_amdgcn_mfma_f32_16x16x32_bf16((a), (b), (c), 0, 0, 0)
; DI void ssd_scan(const Params& P, LAS unsigned char* lds) {
;     ...
;             for (int i = 0; i < 2; ++i) { const int nb = 2 * hb + i; f32x4 sc = {0.f, 0.f, 0.f, 0.f};
; #pragma unroll
;                 for (int ks = 0; ks < 4; ++ks) sc = MFMA16(ca[ks], bbf[i][ks], sc);
;                 const int s = 16 * nb + fr; const float cums = __shfl(cum, s), dts = __shfl(dtv, s);
; #pragma unroll
;                 for (int j = 0; j < 4; ++j) { const int t = 16 * mb + 4 * fq + j; Pm[t * 72 + s] = f2bf(s <= t ? sc[j] * __expf(cumt[j] - cums) * dts : 0.f); } }
;             LDS_BARRIER();
;             float dtn = dtv; bf16x8 cn[4];
; #pragma unroll
;             for (int ks = 0; ks < 4; ++ks) cn[ks] = ca[ks];
;             if (n + 1 < 32) SSD_LOAD(row0 + 64, dtn, cn);
;             f32x4 yi[2], ye[2];
; #pragma unroll
;             for (int i = 0; i < 2; ++i) { yi[i] = (f32x4){0.f, 0.f, 0.f, 0.f}; ye[i] = (f32x4){0.f, 0.f, 0.f, 0.f}; }
; #pragma unroll
;             for (int k2 = 0; k2 < 2; ++k2) { const bf16x8 am = *(const LAS bf16x8*)(Pm + (16 * mb + fr) * 72 + 32 * k2 + 8 * fq);
; #pragma unroll
;                 for (int i = 0; i < 2; ++i) { const bf16x8 bb = *(const LAS bf16x8*)(Xt + (16 * (2 * hb + i) + fr) * 72 + 32 * k2 + 8 * fq); yi[i] = MFMA16(am, bb, yi[i]); } }
; #pragma unroll
;             for (int ks = 0; ks < 4; ++ks)
; #pragma unroll
;                 for (int i = 0; i < 2; ++i) { const bf16x8 bb = *(const LAS bf16x8*)(Sb + (16 * (2 * hb + i) + fr) * 136 + 32 * ks + 8 * fq); ye[i] = MFMA16(ca[ks], bb, ye[i]); }
; #pragma unroll
;             for (int j = 0; j < 4; ++j) { const int tl = 16 * mb + 4 * fq + j, row = row0 + tl; const float ec = __expf(cumt[j]);
; #pragma unroll
;                 for (int i = 0; i < 2; ++i) { const int p = 16 * (2 * hb + i) + fr; const float xv = bf2f(Xt[p * 72 + tl]);
;                     YB[(size_t)row * 2048 + h * 64 + p] = f2bf(yi[i][j] + ec * ye[i][j] + dsk * xv); } }
	v_sub_f32_e32 v54, v52, v58
	ds_write_b16 v160, v34 offset:54304
	v_sub_f32_e32 v34, v52, v38
	v_mul_f32_e32 v54, 0x3fb8aa3b, v54
	v_mul_f32_e32 v34, 0x3fb8aa3b, v34
	v_exp_f32_e32 v54, v54
	v_exp_f32_e32 v34, v34
	ds_bpermute_b32 v51, v138, v79
	ds_bpermute_b32 v50, v139, v79
	v_mul_f32_e32 v54, v55, v54
	v_mul_f32_e32 v34, v35, v34
	v_mul_f32_e32 v54, v54, v59
	v_mul_f32_e32 v34, v34, v39
	v_cvt_pk_bf16_f32 v54, v54, s0
	v_cvt_pk_bf16_f32 v34, v34, s0
	v_cndmask_b32_e64 v54, v54, 0, s[52:53]
	v_cndmask_b32_e64 v34, v34, 0, s[60:61]
	ds_write_b16 v160, v54 offset:54416
	s_waitcnt lgkmcnt(2)
	v_sub_f32_e32 v54, v51, v58
	ds_write_b16 v160, v34 offset:54448
	v_sub_f32_e32 v34, v51, v38
	v_mul_f32_e32 v54, 0x3fb8aa3b, v54
	v_mul_f32_e32 v34, 0x3fb8aa3b, v34
	v_exp_f32_e32 v54, v54
	v_exp_f32_e32 v34, v34
	v_add_u32_e32 v55, v128, v147
	v_mov_b32_e32 v113, v25
	v_mul_f32_e32 v54, v56, v54
	v_mul_f32_e32 v34, v36, v34
	v_mul_f32_e32 v54, v54, v59
	v_mul_f32_e32 v34, v34, v39
	v_cvt_pk_bf16_f32 v54, v54, s0
	v_cvt_pk_bf16_f32 v34, v34, s0
	v_cndmask_b32_e64 v54, v54, 0, s[54:55]
	v_cndmask_b32_e64 v34, v34, 0, s[62:63]
	ds_write_b16 v160, v54 offset:54560
	s_waitcnt lgkmcnt(3)
	v_sub_f32_e32 v54, v50, v58
	ds_write_b16 v160, v34 offset:54592
	v_sub_f32_e32 v34, v50, v38
	v_mul_f32_e32 v54, 0x3fb8aa3b, v54
	v_mul_f32_e32 v34, 0x3fb8aa3b, v34
	v_exp_f32_e32 v54, v54
	v_exp_f32_e32 v34, v34
	v_mul_f32_e32 v54, v57, v54
	v_mul_f32_e32 v34, v37, v34
	v_mul_f32_e32 v54, v54, v59
	v_mul_f32_e32 v34, v34, v39
	v_cvt_pk_bf16_f32 v54, v54, s0
	v_cvt_pk_bf16_f32 v34, v34, s0
	v_cndmask_b32_e64 v54, v54, 0, s[56:57]
	v_cndmask_b32_e64 v34, v34, 0, s[64:65]
	ds_write_b16 v160, v54 offset:54704
	ds_write_b16 v160, v34 offset:54736
	s_waitcnt lgkmcnt(0)
	s_barrier
	ds_read_b128 v[34:37], v129 offset:54272
	v_add_u32_e32 v54, v128, v146
	ds_read_b128 v[38:41], v54 offset:63488
	ds_read_b128 v[42:45], v55 offset:63488
	s_waitcnt lgkmcnt(1)
	v_mfma_f32_16x16x32_bf16 v[38:41], v[34:37], v[38:41], 0
	s_waitcnt lgkmcnt(0)
	v_mfma_f32_16x16x32_bf16 v[42:45], v[34:37], v[42:45], 0
	ds_read_b128 v[46:49], v129 offset:54336
	ds_read_b128 v[34:37], v54 offset:63552
	s_waitcnt lgkmcnt(0)
	v_mfma_f32_16x16x32_bf16 v[34:37], v[46:49], v[34:37], v[38:41]
	s_nop 2
	ds_read_b128 v[38:41], v55 offset:63552
	s_waitcnt lgkmcnt(0)
	v_mfma_f32_16x16x32_bf16 v[38:41], v[46:49], v[38:41], v[42:45]
	s_nop 2
	ds_read_b128 v[42:45], v161
	ds_read_b128 v[46:49], v161 offset:4352
	s_waitcnt lgkmcnt(1)
	v_mfma_f32_16x16x32_bf16 v[42:45], v[30:33], v[42:45], 0
	s_waitcnt lgkmcnt(0)
	v_mfma_f32_16x16x32_bf16 v[30:33], v[30:33], v[46:49], 0
	ds_read_b128 v[46:49], v161 offset:64
	s_waitcnt lgkmcnt(0)
	v_mfma_f32_16x16x32_bf16 v[42:45], v[26:29], v[46:49], v[42:45]
	ds_read_b128 v[46:49], v161 offset:4416
	s_waitcnt lgkmcnt(0)
	v_mfma_f32_16x16x32_bf16 v[26:29], v[26:29], v[46:49], v[30:33]
	s_nop 2
	ds_read_b128 v[30:33], v161 offset:128
	s_waitcnt lgkmcnt(0)
	v_mfma_f32_16x16x32_bf16 v[30:33], v[20:23], v[30:33], v[42:45]
	s_nop 2
	ds_read_b128 v[42:45], v161 offset:4480
	s_waitcnt lgkmcnt(0)
	v_mfma_f32_16x16x32_bf16 v[20:23], v[20:23], v[42:45], v[26:29]
	s_nop 2
	ds_read_b128 v[26:29], v161 offset:192
	s_waitcnt lgkmcnt(0)
	v_mfma_f32_16x16x32_bf16 v[26:29], v[16:19], v[26:29], v[30:33]
	s_nop 2
	ds_read_b128 v[30:33], v161 offset:4544
	s_waitcnt lgkmcnt(0)
	v_mfma_f32_16x16x32_bf16 v[16:19], v[16:19], v[30:33], v[20:23]
	s_nop 2
	v_add_u32_e32 v22, v152, v146
	v_mul_f32_e32 v21, 0x3fb8aa3b, v53
	ds_read_b64 v[22:23], v22 offset:63488
	v_exp_f32_e32 v32, v21
	v_add_u32_e32 v20, s5, v124
	v_ashrrev_i32_e32 v21, 31, v20
	v_lshlrev_b64 v[20:21], 12, v[20:21]
	s_waitcnt lgkmcnt(0)
	v_lshlrev_b32_e32 v30, 16, v22
	v_fma_f32 v26, v32, v26, v34
	v_fmac_f32_e32 v26, v111, v30
	v_lshl_add_u64 v[20:21], v[104:105], 0, v[20:21]
	v_cvt_pk_bf16_f32 v26, v26, s0
	v_lshl_add_u64 v[20:21], v[20:21], 0, s[36:37]
	global_store_short v[20:21], v26, off
	v_add_u32_e32 v26, v152, v147
	ds_read_b64 v[30:31], v26 offset:63488
	v_fma_f32 v16, v32, v16, v38
	v_and_b32_e32 v22, 0xffff0000, v22
	s_waitcnt lgkmcnt(0)
; #define LAS __attribute__((address_space(3)))
; DI unsigned pk2(float lo, float hi) { const f32x2v v = {lo, hi}; const bf16x2v b = __builtin_convertvector(v, bf16x2v); return __builtin_bit_cast(unsigned, b); }
; DI float bf2f(bf16_t b) { return __uint_as_float(((unsigned)b) << 16); }
; DI bf16_t f2bf(float f) { return (bf16_t)(pk2(f, 0.f) & 0xffffu); }
; #define LDS_BARRIER() do { asm volatile("s_waitcnt lgkmcnt(0)" ::: "memory"); __builtin_amdgcn_s_barrier(); asm volatile("" ::: "memory"); } while (0)
; #define MFMA16(a, b, c) __builtin_amdgcn_mfma_f32_16x16x32_bf16((a), (b), (c), 0, 0, 0)
; DI void ssd_scan(const Params& P, LAS unsigned char* lds) {
;     ...
;             for (int j = 0; j < 4; ++j) { const int tl = 16 * mb + 4 * fq + j, row = row0 + tl; const float ec = __expf(cumt[j]);
; #pragma unroll
;                 for (int i = 0; i < 2; ++i) { const int p = 16 * (2 * hb + i) + fr; const float xv = bf2f(Xt[p * 72 + tl]);
;                     YB[(size_t)row * 2048 + h * 64 + p] = f2bf(yi[i][j] + ec * ye[i][j] + dsk * xv); } }
;             { const float ecl = __expf(cl);
; #pragma unroll
;               for (int i = 0; i < 4; ++i) Sacc[i] *= ecl; }
; #pragma unroll
;             for (int k2 = 0; k2 < 2; ++k2) { const bf16x8 am = *(const LAS bf16x8*)(BWt + (16 * wid + fr) * 72 + 32 * k2 + 8 * fq);
; #pragma unroll
;                 for (int i = 0; i < 4; ++i) { const bf16x8 bb = *(const LAS bf16x8*)(Xt + (16 * i + fr) * 72 + 32 * k2 + 8 * fq); Sacc[i] = MFMA16(am, bb, Sacc[i]); } }
; #pragma unroll
;             for (int i = 0; i < 4; ++i) { u32x2 w; w.x = pk2(Sacc[i][0], Sacc[i][1]); w.y = pk2(Sacc[i][2], Sacc[i][3]); *(LAS u32x2*)(Sbn + (16 * i + fr) * 136 + 16 * wid + 4 * fq) = w; }
;             dtv = dtn;
; #pragma unroll
;             for (int ks = 0; ks < 4; ++ks) ca[ks] = cn[ks];
;         }
;     ...
;         float* SO = P.out + OUT_SSMP + ((size_t)(b * 32 + h) * 64) * 128;
; #pragma unroll
;         for (int i = 0; i < 4; ++i) *(f32x4*)(SO + (size_t)(16 * i + fr) * 128 + 16 * wid + 4 * fq) = Sacc[i];
;         LDS_BARRIER();
;     }
	v_lshlrev_b32_e32 v26, 16, v30
	v_fmac_f32_e32 v16, v111, v26
	v_cvt_pk_bf16_f32 v16, v16, s0
	global_store_short v[20:21], v16, off offset:32
	v_mul_f32_e32 v16, 0x3fb8aa3b, v52
	v_exp_f32_e32 v16, v16
	v_add_u32_e32 v20, s5, v142
	v_ashrrev_i32_e32 v21, 31, v20
	v_lshlrev_b64 v[20:21], 12, v[20:21]
	v_fma_f32 v26, v16, v27, v35
	v_fmac_f32_e32 v26, v111, v22
	v_lshl_add_u64 v[20:21], v[104:105], 0, v[20:21]
	v_cvt_pk_bf16_f32 v22, v26, s0
	v_lshl_add_u64 v[20:21], v[20:21], 0, s[36:37]
	global_store_short v[20:21], v22, off
	v_and_b32_e32 v22, 0xffff0000, v30
	v_fma_f32 v16, v16, v17, v39
	v_fmac_f32_e32 v16, v111, v22
	v_cvt_pk_bf16_f32 v16, v16, s0
	v_mul_f32_e32 v17, 0x3fb8aa3b, v51
	global_store_short v[20:21], v16, off offset:32
	v_exp_f32_e32 v20, v17
	v_add_u32_e32 v16, s5, v143
	v_ashrrev_i32_e32 v17, 31, v16
	v_lshlrev_b32_e32 v21, 16, v23
	v_fma_f32 v22, v20, v28, v36
	v_lshlrev_b64 v[16:17], 12, v[16:17]
	v_fmac_f32_e32 v22, v111, v21
	v_lshl_add_u64 v[16:17], v[104:105], 0, v[16:17]
	v_cvt_pk_bf16_f32 v21, v22, s0
	v_lshl_add_u64 v[16:17], v[16:17], 0, s[36:37]
	global_store_short v[16:17], v21, off
	v_lshlrev_b32_e32 v21, 16, v31
	v_fma_f32 v18, v20, v18, v40
	v_fmac_f32_e32 v18, v111, v21
	v_cvt_pk_bf16_f32 v18, v18, s0
	global_store_short v[16:17], v18, off offset:32
	v_mul_f32_e32 v17, 0x3fb8aa3b, v50
	v_exp_f32_e32 v18, v17
	v_add_u32_e32 v16, s5, v144
	v_ashrrev_i32_e32 v17, 31, v16
	v_and_b32_e32 v20, 0xffff0000, v23
	v_fmac_f32_e32 v37, v18, v29
	v_lshlrev_b64 v[16:17], 12, v[16:17]
	v_fmac_f32_e32 v37, v111, v20
	v_lshl_add_u64 v[16:17], v[104:105], 0, v[16:17]
	v_cvt_pk_bf16_f32 v20, v37, s0
	v_lshl_add_u64 v[16:17], v[16:17], 0, s[36:37]
	global_store_short v[16:17], v20, off
	v_and_b32_e32 v20, 0xffff0000, v31
	v_fmac_f32_e32 v41, v18, v19
	v_fmac_f32_e32 v41, v111, v20
	v_cvt_pk_bf16_f32 v18, v41, s0
	global_store_short v[16:17], v18, off offset:32
	v_mul_f32_e32 v16, 0x3fb8aa3b, v78
	v_exp_f32_e32 v16, v16
	v_add_u32_e32 v26, v128, v149
	ds_read_b128 v[20:23], v26 offset:63488
	s_ashr_i32 s5, s4, 31
	v_pk_mul_f32 v[2:3], v[2:3], v[16:17] op_sel_hi:[1,0]
	v_pk_mul_f32 v[0:1], v[0:1], v[16:17] op_sel_hi:[1,0]
	v_pk_mul_f32 v[6:7], v[6:7], v[16:17] op_sel_hi:[1,0]
	v_pk_mul_f32 v[4:5], v[4:5], v[16:17] op_sel_hi:[1,0]
	v_pk_mul_f32 v[14:15], v[14:15], v[16:17] op_sel_hi:[1,0]
	v_pk_mul_f32 v[12:13], v[12:13], v[16:17] op_sel_hi:[1,0]
	v_pk_mul_f32 v[10:11], v[10:11], v[16:17] op_sel_hi:[1,0]
	v_pk_mul_f32 v[8:9], v[8:9], v[16:17] op_sel_hi:[1,0]
	ds_read_b128 v[16:19], v153
	s_waitcnt lgkmcnt(0)
	v_mfma_f32_16x16x32_bf16 v[0:3], v[16:19], v[20:23], v[0:3]
	ds_read_b128 v[20:23], v162 offset:63488
	s_lshl_b64 s[16:17], s[4:5], 15
	v_mov_b32_e32 v111, v25
	s_waitcnt lgkmcnt(0)
	v_mfma_f32_16x16x32_bf16 v[4:7], v[16:19], v[20:23], v[4:7]
	ds_read_b128 v[20:23], v163 offset:63488
	s_waitcnt lgkmcnt(0)
	v_mfma_f32_16x16x32_bf16 v[12:15], v[16:19], v[20:23], v[12:15]
	ds_read_b128 v[20:23], v164 offset:63488
	s_waitcnt lgkmcnt(0)
	v_mfma_f32_16x16x32_bf16 v[8:11], v[16:19], v[20:23], v[8:11]
	ds_read_b128 v[16:19], v153 offset:64
	ds_read_b128 v[20:23], v26 offset:63552
	s_load_dwordx2 s[14:15], s[0:1], 0x150
	s_waitcnt lgkmcnt(0)
	s_add_u32 s5, s14, s16
	v_mfma_f32_16x16x32_bf16 v[0:3], v[16:19], v[20:23], v[0:3]
	ds_read_b128 v[20:23], v162 offset:63552
	s_addc_u32 s13, s15, s17
	s_add_u32 s14, s5, s22
	s_waitcnt lgkmcnt(0)
	v_mfma_f32_16x16x32_bf16 v[4:7], v[16:19], v[20:23], v[4:7]
	ds_read_b128 v[20:23], v163 offset:63552
	s_addc_u32 s15, s13, 0
	s_mov_b32 s5, 0x8ff8000
	s_waitcnt lgkmcnt(0)
	v_mfma_f32_16x16x32_bf16 v[12:15], v[16:19], v[20:23], v[12:15]
	ds_read_b128 v[20:23], v164 offset:63552
	s_waitcnt lgkmcnt(0)
	v_mfma_f32_16x16x32_bf16 v[8:11], v[16:19], v[20:23], v[8:11]
	v_cvt_pk_bf16_f32 v16, v0, v1
	v_cvt_pk_bf16_f32 v17, v2, v3
	v_add_u32_e32 v18, v154, v150
	ds_write_b64 v18, v[16:17] offset:18432
	v_cvt_pk_bf16_f32 v16, v4, v5
	v_cvt_pk_bf16_f32 v17, v6, v7
	ds_write_b64 v18, v[16:17] offset:22784
	v_cvt_pk_bf16_f32 v16, v12, v13
	v_cvt_pk_bf16_f32 v17, v14, v15
	ds_write_b64 v18, v[16:17] offset:27136
	v_cvt_pk_bf16_f32 v16, v8, v9
	v_cvt_pk_bf16_f32 v17, v10, v11
	ds_write_b64 v18, v[16:17] offset:31488
	v_lshl_add_u64 v[16:17], s[14:15], 0, v[110:111]
	v_lshl_add_u64 v[16:17], v[16:17], 0, v[112:113]
	v_add_co_u32_e32 v18, vcc, s5, v16
	s_mov_b32 s5, 0x8ffa000
	s_nop 0
	v_addc_co_u32_e32 v19, vcc, 0, v17, vcc
	global_store_dwordx4 v[18:19], v[0:3], off
	v_readlane_b32 s14, v255, 13
	v_readlane_b32 s15, v255, 14
	v_add_co_u32_e32 v0, vcc, s5, v16
	s_mov_b32 s5, 0x8ffc000
	s_nop 0
	v_addc_co_u32_e32 v1, vcc, 0, v17, vcc
	global_store_dwordx4 v[0:1], v[4:7], off
	v_add_co_u32_e32 v0, vcc, s5, v16
	s_nop 1
	v_addc_co_u32_e32 v1, vcc, 0, v17, vcc
	global_store_dwordx4 v[0:1], v[12:15], off
	v_add_co_u32_e32 v0, vcc, 0x8ffe000, v16
	s_nop 1
	v_addc_co_u32_e32 v1, vcc, 0, v17, vcc
	global_store_dwordx4 v[0:1], v[8:11], off
	s_waitcnt lgkmcnt(0)
	s_barrier
	s_load_dword s5, s[14:15], 0x0
	s_waitcnt lgkmcnt(0)
	s_add_i32 s4, s5, s4
	s_cmpk_gt_i32 s4, 0xff
	s_cbranch_scc0 .LBB0_174
